# LRU out-proj GEMM: residual x requested with the first K tiles and used as the initial f32 accumulator value (x + sum of products, f32 throughout) instead of a load+add after the K loop
# baseline (speedup 1.0000x reference)
; template <class Epi, class Sched, bool ALIGN_EPI = false, bool SP2 = false>
; __device__ __forceinline__ void gemm_phase(PG8_LAS unsigned char* lds, const Gemm g, const Sched& S, const Epi& E) {
;     const int tid = threadIdx.x, wid = __builtin_amdgcn_readfirstlane(tid >> 6), lane = tid & 63, wr = wid >> 2, wc = wid & 3, fr = lane & 15, fq = lane >> 4;
;     const int K = g.K, nt = K / BK;
;     unsigned voffA[2], voffB[2];
; #pragma unroll
;     for (int i = 0; i < 2; ++i) { int R, C; stage_rc(tid * 16 + i * 8192, R, C); const int Rb = Epi::PERM ? ((R & ~31) + perm32(R & 31)) : R;
;         voffA[i] = (unsigned)(R * K + C) * 2u; voffB[i] = (unsigned)(Rb * K + C) * 2u; }
;     const size_t kstep = (size_t)(BK * 2);
;     const size_t hstep = (size_t)HALF * K * 2;
;     const size_t tstep = 2 * hstep;
;     const unsigned ldsw = (unsigned)wid * 1024u;
;     const int aoff = lds_byte(wr * 64 + fr, fq * 8), boff = lds_byte(wc * 32 + fr, fq * 8);
;     ...
;     Unit cur, nxt; int ui = 0;
;     if (!S.next(0, cur)) return;
;     f32x4 acc[2][2][4][2];
; #pragma unroll
;     for (int a = 0; a < 2; ++a)
; #pragma unroll
;         for (int b = 0; b < 2; ++b)
; #pragma unroll
;             for (int m = 0; m < 4; ++m)
; #pragma unroll
;                 for (int n = 0; n < 2; ++n) acc[a][b][m][n] = (f32x4){0.f, 0.f, 0.f, 0.f};
;     bf16x8 At[4][2], B0[2][2], B1[2][2];
;     const char* cA = (const char*)g.A + (size_t)cur.pm * tstep; const char* cB = (const char*)g.Bt + (size_t)cur.pn * tstep;
;     S.a_ready(cur);
;     if constexpr (SP2) {
;         PG8_STAGE(PG8_SB(0, 0), cB, voffB); PG8_STAGE(PG8_SB(0, 1), cB + hstep, voffB); PG8_STAGE(PG8_SA(0, 0), cA, voffA); PG8_STAGE(PG8_SA(0, 1), cA + hstep, voffA);
;         if (wr == 1) PG8_BAR;
;         PG8_WAIT_V(2); PG8_BAR;
;         PG8_STAGE(PG8_SB(1, 0), cB + kstep, voffB); PG8_STAGE(PG8_SA(1, 0), cA + kstep, voffA); PG8_STAGE(PG8_SB(1, 1), cB + hstep + kstep, voffB);
;         PG8_WAIT_V(6); PG8_BAR;
;     } else {
;         PG8_STAGE(PG8_SB(0, 0), cB, voffB); PG8_STAGE(PG8_SA(0, 0), cA, voffA); PG8_STAGE(PG8_SB(0, 1), cB + hstep, voffB); PG8_STAGE(PG8_SA(0, 1), cA + hstep, voffA);
;         if (wr == 1) PG8_BAR;
;         PG8_WAIT_V(4); PG8_BAR;
;         PG8_STAGE(PG8_SB(1, 0), cB + kstep, voffB); PG8_STAGE(PG8_SA(1, 0), cA + kstep, voffA); PG8_STAGE(PG8_SB(1, 1), cB + hstep + kstep, voffB);
.LBB0_388:
	s_andn2_b64 vcc, exec, s[2:3]
	s_cbranch_vccnz .LBB0_424
	v_lshrrev_b32_e32 v2, 1, v184
	v_lshrrev_b32_e32 v3, 5, v184
	v_and_b32_e32 v2, 24, v2
	v_and_b32_e32 v3, 4, v3
	v_bfe_u32 v4, v184, 2, 2
	v_and_b32_e32 v0, 32, v184
	v_bfe_u32 v1, v184, 2, 4
	v_or3_b32 v2, v3, v4, v2
	v_lshrrev_b32_e32 v3, 3, v184
	s_movk_i32 s3, 0x70
	v_bitop3_b32 v8, v186, v0, 48 bitop3:0x6c
	v_and_b32_e32 v9, 64, v184
	v_and_or_b32 v4, v3, s3, v1
	s_movk_i32 s3, 0x60
	v_or_b32_e32 v0, v8, v9
	v_and_or_b32 v3, v3, s3, v2
	v_lshrrev_b32_e32 v0, 1, v0
	v_mul_u32_u24_e32 v3, 0x500, v3
	v_or_b32_e32 v3, v3, v0
	s_add_u32 s25, s54, 0x8c00000
	v_lshlrev_b32_e32 v190, 1, v3
	v_add_u32_e32 v3, 0x2000, v186
	s_addc_u32 s26, s55, 0
	v_lshrrev_b32_e32 v3, 7, v3
	s_movk_i32 s3, 0xf0
	s_add_u32 s27, s54, 0x800000
	v_and_or_b32 v1, v3, s3, v1
	s_movk_i32 s3, 0xe0
	s_addc_u32 s28, s55, 0
	v_and_or_b32 v2, v3, s3, v2
	s_lshr_b32 s3, s24, 6
	s_lshr_b32 s2, s24, 8
	s_lshl_b32 s29, s3, 10
	s_mul_i32 s5, s48, 0xa0000
	v_mul_u32_u24_e32 v11, 0x500, v1
	s_mul_hi_i32 s4, s48, 0xa0000
	s_add_u32 s20, s27, s5
	v_or_b32_e32 v1, v11, v0
	s_addc_u32 s21, s28, s4
	s_add_i32 s30, s29, 0
	v_mul_u32_u24_e32 v10, 0x500, v4
	v_lshlrev_b32_e32 v192, 1, v1
	v_mul_u32_u24_e32 v1, 0x500, v2
	s_add_i32 m0, s30, 0x10000
	v_or_b32_e32 v4, v0, v10
	v_or_b32_e32 v0, v1, v0
	v_and_b32_e32 v212, 15, v184
	v_lshl_or_b32 v212, s2, 6, v212
	v_bfe_u32 v213, v184, 4, 2
	s_lshl_b32 s71, s3, 5
	s_and_b32 s71, s71, 0x60
	v_lshl_or_b32 v213, v213, 3, s71
	s_add_u32 s72, s54, 0x1800000
	s_addc_u32 s73, s55, 0
	v_lshl_add_u32 v228, s49, 8, v212
	v_lshl_or_b32 v229, s48, 8, v213
	v_lshlrev_b32_e32 v228, 11, v228
	v_lshl_add_u32 v214, v229, 1, v228
	v_add_u32_e32 v215, 0x8000, v214
	v_add_u32_e32 v216, 0x10000, v214
	v_add_u32_e32 v217, 0x18000, v214
	v_add_u32_e32 v218, 0x40000, v214
	v_add_u32_e32 v219, 0x48000, v214
	v_add_u32_e32 v220, 0x50000, v214
	v_add_u32_e32 v221, 0x58000, v214
	global_load_dwordx4 v[100:103], v214, s[72:73]
	global_load_dwordx4 v[108:111], v214, s[72:73] offset:256
	global_load_dwordx4 v[120:123], v215, s[72:73]
	global_load_dwordx4 v[132:135], v215, s[72:73] offset:256
	global_load_dwordx4 v[144:147], v216, s[72:73]
	global_load_dwordx4 v[148:151], v216, s[72:73] offset:256
	global_load_dwordx4 v[152:155], v217, s[72:73]
	global_load_dwordx4 v[156:159], v217, s[72:73] offset:256
	global_load_dwordx4 v[160:163], v218, s[72:73]
	global_load_dwordx4 v[164:167], v218, s[72:73] offset:256
	global_load_dwordx4 v[168:171], v219, s[72:73]
	global_load_dwordx4 v[172:175], v219, s[72:73] offset:256
	global_load_dwordx4 v[176:179], v220, s[72:73]
	global_load_dwordx4 v[180:183], v220, s[72:73] offset:256
	global_load_dwordx4 v[204:207], v221, s[72:73]
	global_load_dwordx4 v[208:211], v221, s[72:73] offset:256
	s_mov_b32 s94, 1
	global_load_lds_dwordx4 v190, s[20:21]
	s_add_i32 m0, s30, 0x12000
	v_lshlrev_b32_e32 v194, 1, v0
	s_add_u32 s4, s20, 0x50000
	global_load_lds_dwordx4 v194, s[20:21]
	s_addc_u32 s5, s21, 0
	s_add_i32 m0, s30, 0x14000
	s_mul_i32 s7, s49, 0xa0000
	global_load_lds_dwordx4 v190, s[4:5]
	s_add_i32 m0, s30, 0x16000
	s_mul_hi_i32 s6, s49, 0xa0000
	s_add_u32 s18, s25, s7
	s_addc_u32 s19, s26, s6
	s_add_i32 s31, s30, 0x2000
	v_lshlrev_b32_e32 v188, 1, v4
	global_load_lds_dwordx4 v194, s[4:5]
	s_mov_b32 m0, s30
	s_add_u32 s4, s18, 0x50000
	global_load_lds_dwordx4 v188, s[18:19]
	s_mov_b32 m0, s31
	s_addc_u32 s5, s19, 0
	s_add_i32 s34, s30, 0x4000
	global_load_lds_dwordx4 v192, s[18:19]
	s_mov_b32 m0, s34
	s_add_i32 s35, s30, 0x6000
	global_load_lds_dwordx4 v188, s[4:5]
	s_mov_b32 m0, s35
	v_mov_b32_e32 v191, 0
	global_load_lds_dwordx4 v192, s[4:5]
	v_mov_b32_e32 v195, v191
	v_mov_b32_e32 v189, v191
	v_mov_b32_e32 v193, v191
	s_mov_b32 s36, 0
	v_lshl_add_u64 v[6:7], s[20:21], 0, v[190:191]
	v_lshl_add_u64 v[4:5], s[20:21], 0, v[194:195]
	v_lshl_add_u64 v[2:3], s[18:19], 0, v[188:189]
	s_cmp_lg_u32 s2, 1
	v_lshl_add_u64 v[0:1], s[18:19], 0, v[192:193]
	s_cbranch_scc1 .LBB0_391
	s_barrier

;     __device__ __forceinline__ void operator()(const f32x4 (&acc)[2][2][4][2], const Unit& u, int wr, int wc, int fr, int fq) const {
;     ...
;                 for (int bj = 0; bj < 2; ++bj) rb[ai][m][bj] = *(const u32x4*)(base + (size_t)(row0 + ai * HALF + m * 16) * ldc + col0 + bj * HALF);
;         asm volatile("" ::: "memory");
; #pragma unroll
;         for (int ai = 0; ai < 2; ++ai)
; #pragma unroll
;             for (int m = 0; m < 4; ++m) { const int row = row0 + ai * HALF + m * 16; float s = 0.f;
; #pragma unroll
;                 for (int bj = 0; bj < 2; ++bj) { const u32x4 w = rb[ai][m][bj];
;                     const f32x4 v0 = acc[ai][bj][m][0] + (f32x4){__uint_as_float(w.x << 16), __uint_as_float(w.x & 0xffff0000u), __uint_as_float(w.y << 16), __uint_as_float(w.y & 0xffff0000u)};
;                     const f32x4 v1 = acc[ai][bj][m][1] + (f32x4){__uint_as_float(w.z << 16), __uint_as_float(w.z & 0xffff0000u), __uint_as_float(w.w << 16), __uint_as_float(w.w & 0xffff0000u)};
; template <class Epi, class Sched, bool ALIGN_EPI = false, bool SP2 = false>
; __device__ __forceinline__ void gemm_phase(PG8_LAS unsigned char* lds, const Gemm g, const Sched& S, const Epi& E) {
;     ...
;         for (int a = 0; a < 2; ++a)
; #pragma unroll
;             for (int b = 0; b < 2; ++b)
; #pragma unroll
;                 for (int m = 0; m < 4; ++m)
; #pragma unroll
;                     for (int n = 0; n < 2; ++n) acc[a][b][m][n] = (f32x4){0.f, 0.f, 0.f, 0.f};
;         cur = nxt; cA = nA; cB = nB; ++ui;
.LBB0_403:
	s_cmp_eq_u32 s94, 1
	s_cbranch_scc1 .Lp4_resid_have
	v_lshl_add_u32 v228, s49, 8, v185
	v_lshl_or_b32 v229, s48, 8, v222
	v_lshlrev_b32_e32 v228, 11, v228
	v_lshl_add_u32 v214, v229, 1, v228
	v_add_u32_e32 v215, 0x8000, v214
	v_add_u32_e32 v216, 0x10000, v214
	v_add_u32_e32 v217, 0x18000, v214
	v_add_u32_e32 v218, 0x40000, v214
	v_add_u32_e32 v219, 0x48000, v214
	v_add_u32_e32 v220, 0x50000, v214
	v_add_u32_e32 v221, 0x58000, v214
	global_load_dwordx4 v[100:103], v214, s[12:13]
	global_load_dwordx4 v[108:111], v214, s[12:13] offset:256
	global_load_dwordx4 v[120:123], v215, s[12:13]
	global_load_dwordx4 v[132:135], v215, s[12:13] offset:256
	global_load_dwordx4 v[144:147], v216, s[12:13]
	global_load_dwordx4 v[148:151], v216, s[12:13] offset:256
	global_load_dwordx4 v[152:155], v217, s[12:13]
	global_load_dwordx4 v[156:159], v217, s[12:13] offset:256
	global_load_dwordx4 v[160:163], v218, s[12:13]
	global_load_dwordx4 v[164:167], v218, s[12:13] offset:256
	global_load_dwordx4 v[168:171], v219, s[12:13]
	global_load_dwordx4 v[172:175], v219, s[12:13] offset:256
	global_load_dwordx4 v[176:179], v220, s[12:13]
	global_load_dwordx4 v[180:183], v220, s[12:13] offset:256
	global_load_dwordx4 v[204:207], v221, s[12:13]
	global_load_dwordx4 v[208:211], v221, s[12:13] offset:256
	s_waitcnt vmcnt(0)
.Lp4_resid_have:
	s_mov_b32 s94, 0
	s_add_u32 s18, s18, 0x50080
	s_addc_u32 s19, s19, 0
	s_add_u32 s50, s20, 0x100
	v_lshlrev_b32_e32 v0, 16, v210
	v_and_b32_e32 v1, 0xffff0000, v210
	v_lshlrev_b32_e32 v2, 16, v211
	v_and_b32_e32 v3, 0xffff0000, v211
	v_lshlrev_b32_e32 v4, 16, v208
	v_and_b32_e32 v5, 0xffff0000, v208
	v_lshlrev_b32_e32 v6, 16, v209
	v_and_b32_e32 v7, 0xffff0000, v209
	v_lshlrev_b32_e32 v8, 16, v206
	v_and_b32_e32 v9, 0xffff0000, v206
	v_lshlrev_b32_e32 v10, 16, v207
	v_and_b32_e32 v11, 0xffff0000, v207
	v_lshlrev_b32_e32 v12, 16, v204
	v_and_b32_e32 v13, 0xffff0000, v204
	v_lshlrev_b32_e32 v14, 16, v205
	v_and_b32_e32 v15, 0xffff0000, v205
	v_lshlrev_b32_e32 v16, 16, v182
	v_and_b32_e32 v17, 0xffff0000, v182
	v_lshlrev_b32_e32 v18, 16, v183
	v_and_b32_e32 v19, 0xffff0000, v183
	v_lshlrev_b32_e32 v20, 16, v180
	v_and_b32_e32 v21, 0xffff0000, v180
	v_lshlrev_b32_e32 v22, 16, v181
	v_and_b32_e32 v23, 0xffff0000, v181
	v_lshlrev_b32_e32 v24, 16, v178
	v_and_b32_e32 v25, 0xffff0000, v178
	v_lshlrev_b32_e32 v26, 16, v179
	v_and_b32_e32 v27, 0xffff0000, v179
	v_lshlrev_b32_e32 v28, 16, v176
	v_and_b32_e32 v29, 0xffff0000, v176
	v_lshlrev_b32_e32 v30, 16, v177
	v_and_b32_e32 v31, 0xffff0000, v177
	v_lshlrev_b32_e32 v32, 16, v174
	v_and_b32_e32 v33, 0xffff0000, v174
	v_lshlrev_b32_e32 v34, 16, v175
	v_and_b32_e32 v35, 0xffff0000, v175
	v_lshlrev_b32_e32 v36, 16, v172
	v_and_b32_e32 v37, 0xffff0000, v172
	v_lshlrev_b32_e32 v38, 16, v173
	v_and_b32_e32 v39, 0xffff0000, v173
	v_lshlrev_b32_e32 v40, 16, v170
	v_and_b32_e32 v41, 0xffff0000, v170
	v_lshlrev_b32_e32 v42, 16, v171
	v_and_b32_e32 v43, 0xffff0000, v171
	v_lshlrev_b32_e32 v44, 16, v168
	v_and_b32_e32 v45, 0xffff0000, v168
	v_lshlrev_b32_e32 v46, 16, v169
	v_and_b32_e32 v47, 0xffff0000, v169
	v_lshlrev_b32_e32 v48, 16, v166
	v_and_b32_e32 v49, 0xffff0000, v166
	v_lshlrev_b32_e32 v50, 16, v167
	v_and_b32_e32 v51, 0xffff0000, v167
	v_lshlrev_b32_e32 v52, 16, v164
	v_and_b32_e32 v53, 0xffff0000, v164
	v_lshlrev_b32_e32 v54, 16, v165
	v_and_b32_e32 v55, 0xffff0000, v165
	v_lshlrev_b32_e32 v56, 16, v162
	v_and_b32_e32 v57, 0xffff0000, v162
	v_lshlrev_b32_e32 v58, 16, v163
	v_and_b32_e32 v59, 0xffff0000, v163
	v_lshlrev_b32_e32 v60, 16, v160
	v_and_b32_e32 v61, 0xffff0000, v160
	v_lshlrev_b32_e32 v62, 16, v161
	v_and_b32_e32 v63, 0xffff0000, v161
	v_lshlrev_b32_e32 v64, 16, v158
	v_and_b32_e32 v65, 0xffff0000, v158
	v_lshlrev_b32_e32 v66, 16, v159
	v_and_b32_e32 v67, 0xffff0000, v159
	v_lshlrev_b32_e32 v68, 16, v156
	v_and_b32_e32 v69, 0xffff0000, v156
	v_lshlrev_b32_e32 v70, 16, v157
	v_and_b32_e32 v71, 0xffff0000, v157
	v_lshlrev_b32_e32 v72, 16, v154
	v_and_b32_e32 v73, 0xffff0000, v154
	v_lshlrev_b32_e32 v74, 16, v155
	v_and_b32_e32 v75, 0xffff0000, v155
	v_lshlrev_b32_e32 v76, 16, v152
	v_and_b32_e32 v77, 0xffff0000, v152
	v_lshlrev_b32_e32 v78, 16, v153
	v_and_b32_e32 v79, 0xffff0000, v153
	v_lshlrev_b32_e32 v80, 16, v150
	v_and_b32_e32 v81, 0xffff0000, v150
	v_lshlrev_b32_e32 v82, 16, v151
	v_and_b32_e32 v83, 0xffff0000, v151
	v_lshlrev_b32_e32 v84, 16, v148
	v_and_b32_e32 v85, 0xffff0000, v148
	v_lshlrev_b32_e32 v86, 16, v149
	v_and_b32_e32 v87, 0xffff0000, v149
	v_lshlrev_b32_e32 v88, 16, v146
	v_and_b32_e32 v89, 0xffff0000, v146
	v_lshlrev_b32_e32 v90, 16, v147
	v_and_b32_e32 v91, 0xffff0000, v147
	v_lshlrev_b32_e32 v92, 16, v144
	v_and_b32_e32 v93, 0xffff0000, v144
	v_lshlrev_b32_e32 v94, 16, v145
	v_and_b32_e32 v95, 0xffff0000, v145
	v_lshlrev_b32_e32 v96, 16, v134
	v_and_b32_e32 v97, 0xffff0000, v134
	v_lshlrev_b32_e32 v98, 16, v135
	v_and_b32_e32 v99, 0xffff0000, v135
	v_lshlrev_b32_e32 v104, 16, v132
	v_and_b32_e32 v105, 0xffff0000, v132
	v_lshlrev_b32_e32 v106, 16, v133
	v_and_b32_e32 v107, 0xffff0000, v133
	v_lshlrev_b32_e32 v112, 16, v122
	v_and_b32_e32 v113, 0xffff0000, v122
	v_lshlrev_b32_e32 v114, 16, v123
	v_and_b32_e32 v115, 0xffff0000, v123
	v_lshlrev_b32_e32 v116, 16, v120
	v_and_b32_e32 v117, 0xffff0000, v120
	v_lshlrev_b32_e32 v118, 16, v121
	v_and_b32_e32 v119, 0xffff0000, v121
	v_lshlrev_b32_e32 v124, 16, v110
	v_and_b32_e32 v125, 0xffff0000, v110
	v_lshlrev_b32_e32 v126, 16, v111
	v_and_b32_e32 v127, 0xffff0000, v111
	v_lshlrev_b32_e32 v128, 16, v108
	v_and_b32_e32 v129, 0xffff0000, v108
	v_lshlrev_b32_e32 v130, 16, v109
	v_and_b32_e32 v131, 0xffff0000, v109
	v_lshlrev_b32_e32 v136, 16, v102
	v_and_b32_e32 v137, 0xffff0000, v102
	v_lshlrev_b32_e32 v138, 16, v103
	v_and_b32_e32 v139, 0xffff0000, v103
	v_lshlrev_b32_e32 v140, 16, v100
	v_and_b32_e32 v141, 0xffff0000, v100
	v_lshlrev_b32_e32 v142, 16, v101
	v_and_b32_e32 v143, 0xffff0000, v101
	s_addc_u32 s51, s21, 0
	s_mov_b32 s58, -2
	s_waitcnt lgkmcnt(0)
; #define PG8_STAGE(bufoff, gbase, voff) do { _Pragma("unroll") for (int _i = 0; _i < 2; ++_i) \
;         __builtin_amdgcn_global_load_lds((const unsigned*)((const char*)(gbase) + (voff)[_i]), (PG8_LAS unsigned*)(lds + (bufoff) + ldsw + _i * 8192), 16, 0, 0); } while (0)
; #define PG8_LDA(dst, b, h) do { _Pragma("unroll") for (int m = 0; m < 4; ++m) _Pragma("unroll") for (int k = 0; k < 2; ++k) dst[m][k] = *(const PG8_LAS bf16x8*)(lds + PG8_SA(b, h) + aoff + m * 2048 + k * 1024); } while (0)
; #define PG8_LDB(dst, b, h) do { _Pragma("unroll") for (int n = 0; n < 2; ++n) _Pragma("unroll") for (int k = 0; k < 2; ++k) dst[n][k] = *(const PG8_LAS bf16x8*)(lds + PG8_SB(b, h) + boff + n * 2048 + k * 1024); } while (0)
; #define PG8_MMA(ai, bj, At, Bt) do { __builtin_amdgcn_s_setprio(1); _Pragma("unroll") for (int m = 0; m < 4; ++m) _Pragma("unroll") for (int n = 0; n < 2; ++n) _Pragma("unroll") for (int k = 0; k < 2; ++k) \
;         acc[ai][bj][m][n] = __builtin_amdgcn_mfma_f32_16x16x32_bf16(Bt[n][k], At[m][k], acc[ai][bj][m][n], 0, 0, 0); __builtin_amdgcn_s_setprio(0); } while (0)
; template <class Epi, class Sched, bool ALIGN_EPI = false, bool SP2 = false>
; __device__ __forceinline__ void gemm_phase(PG8_LAS unsigned char* lds, const Gemm g, const Sched& S, const Epi& E) {
;     ...
;             const bool last = (t == nt - 2);
;             const char* a1 = cA + (size_t)(t + 1) * kstep;
;             const char* a2 = last ? nA : cA + (size_t)(t + 2) * kstep; const char* b2 = last ? nB : cB + (size_t)(t + 2) * kstep;
;             const char* a3 = a2 + kstep; const char* b3 = b2 + kstep;
;             if (last && has_next) S.a_ready(nxt);
;             if constexpr (SP2) {
;             PG8_LDB(B0, 0, 0); PG8_LDB(B1, 0, 1); PG8_SCHED; PG8_LDA(At, 0, 0); PG8_STAGE(PG8_SA(1, 1), a1 + hstep, voffA);
;             PG8_WAIT_V(8); PG8_WAIT_L(0); PG8_BAR; PG8_MMA(0, 0, At, B0); PG8_MMA(0, 1, At, B1); PG8_BAR; PG8_SCHED;
;             PG8_LDA(At, 0, 1); PG8_STAGE(PG8_SB(0, 0), b2, voffB); PG8_STAGE(PG8_SB(0, 1), b2 + hstep, voffB); PG8_STAGE(PG8_SA(0, 0), a2, voffA);
;     ...
;         for (int a = 0; a < 2; ++a)
; #pragma unroll
;             for (int b = 0; b < 2; ++b)
; #pragma unroll
;                 for (int m = 0; m < 4; ++m)
; #pragma unroll
;                     for (int n = 0; n < 2; ++n) acc[a][b][m][n] = (f32x4){0.f, 0.f, 0.f, 0.f};
.LBB0_404:
	ds_read_b128 v[100:103], v223
	ds_read_b128 v[108:111], v223 offset:1024
	ds_read_b128 v[120:123], v223 offset:2048
	ds_read_b128 v[132:135], v223 offset:3072
	ds_read_b128 v[144:147], v224
	ds_read_b128 v[148:151], v224 offset:1024
	ds_read_b128 v[152:155], v224 offset:2048
	ds_read_b128 v[156:159], v224 offset:3072
	s_add_u32 s20, s18, 0xfffb0080
	s_addc_u32 s21, s19, -1
	s_cmp_eq_u32 s58, 16
	s_cselect_b32 s23, s7, s21
	s_cselect_b32 s22, s6, s20
	s_cselect_b32 s21, s9, s51
	s_cselect_b32 s20, s8, s50
	v_lshl_add_u64 v[212:213], s[18:19], 0, v[196:197]
	s_add_i32 m0, s30, 0xc000
	ds_read_b128 v[160:163], v225
	ds_read_b128 v[164:167], v225 offset:1024
	ds_read_b128 v[168:171], v225 offset:2048
	ds_read_b128 v[172:175], v225 offset:3072
	ds_read_b128 v[176:179], v225 offset:4096
	ds_read_b128 v[180:183], v225 offset:5120
	ds_read_b128 v[204:207], v225 offset:6144
	ds_read_b128 v[208:211], v225 offset:7168
	global_load_lds_dwordx4 v[212:213], off
	v_lshl_add_u64 v[212:213], s[18:19], 0, v[198:199]
	s_add_i32 m0, s30, 0xe000
	s_nop 0
	global_load_lds_dwordx4 v[212:213], off
	s_waitcnt vmcnt(8)
	s_waitcnt lgkmcnt(0)
	s_barrier
	s_setprio 1
	s_waitcnt lgkmcnt(0)
	v_mfma_f32_16x16x32_bf16 v[140:143], v[100:103], v[160:163], v[140:143]
	v_mfma_f32_16x16x32_bf16 v[136:139], v[120:123], v[160:163], v[136:139]
	v_mfma_f32_16x16x32_bf16 v[116:119], v[100:103], v[168:171], v[116:119]
	v_mfma_f32_16x16x32_bf16 v[112:115], v[120:123], v[168:171], v[112:115]
	v_mfma_f32_16x16x32_bf16 v[92:95], v[100:103], v[176:179], v[92:95]
	v_mfma_f32_16x16x32_bf16 v[88:91], v[120:123], v[176:179], v[88:91]
	v_mfma_f32_16x16x32_bf16 v[76:79], v[100:103], v[204:207], v[76:79]
	v_mfma_f32_16x16x32_bf16 v[72:75], v[120:123], v[204:207], v[72:75]
	v_mfma_f32_16x16x32_bf16 v[140:143], v[108:111], v[164:167], v[140:143]
	v_mfma_f32_16x16x32_bf16 v[136:139], v[132:135], v[164:167], v[136:139]
	v_mfma_f32_16x16x32_bf16 v[116:119], v[108:111], v[172:175], v[116:119]
	v_mfma_f32_16x16x32_bf16 v[112:115], v[132:135], v[172:175], v[112:115]
	v_mfma_f32_16x16x32_bf16 v[92:95], v[108:111], v[180:183], v[92:95]
	v_mfma_f32_16x16x32_bf16 v[88:91], v[132:135], v[180:183], v[88:91]
	v_mfma_f32_16x16x32_bf16 v[76:79], v[108:111], v[208:211], v[76:79]
	v_mfma_f32_16x16x32_bf16 v[72:75], v[132:135], v[208:211], v[72:75]
	s_setprio 0
	s_setprio 1
	v_mfma_f32_16x16x32_bf16 v[128:131], v[144:147], v[160:163], v[128:131]
	v_mfma_f32_16x16x32_bf16 v[124:127], v[152:155], v[160:163], v[124:127]
	v_mfma_f32_16x16x32_bf16 v[104:107], v[144:147], v[168:171], v[104:107]
	v_mfma_f32_16x16x32_bf16 v[96:99], v[152:155], v[168:171], v[96:99]
	v_mfma_f32_16x16x32_bf16 v[84:87], v[144:147], v[176:179], v[84:87]
	v_mfma_f32_16x16x32_bf16 v[80:83], v[152:155], v[176:179], v[80:83]
	v_mfma_f32_16x16x32_bf16 v[68:71], v[144:147], v[204:207], v[68:71]
	v_mfma_f32_16x16x32_bf16 v[64:67], v[152:155], v[204:207], v[64:67]
	v_mfma_f32_16x16x32_bf16 v[128:131], v[148:151], v[164:167], v[128:131]
	v_mfma_f32_16x16x32_bf16 v[124:127], v[156:159], v[164:167], v[124:127]
	v_mfma_f32_16x16x32_bf16 v[104:107], v[148:151], v[172:175], v[104:107]
	v_mfma_f32_16x16x32_bf16 v[96:99], v[156:159], v[172:175], v[96:99]
	v_mfma_f32_16x16x32_bf16 v[84:87], v[148:151], v[180:183], v[84:87]
	v_mfma_f32_16x16x32_bf16 v[80:83], v[156:159], v[180:183], v[80:83]
	v_mfma_f32_16x16x32_bf16 v[68:71], v[148:151], v[208:211], v[68:71]
	v_mfma_f32_16x16x32_bf16 v[64:67], v[156:159], v[208:211], v[64:67]
	s_setprio 0
	s_barrier
	s_add_i32 s69, s44, s29
	v_lshl_add_u64 v[212:213], s[20:21], 0, v[190:191]
	s_mov_b32 m0, s69
	ds_read_b128 v[160:163], v225 offset:16384
	ds_read_b128 v[164:167], v225 offset:17408
	ds_read_b128 v[168:171], v225 offset:18432
	ds_read_b128 v[172:175], v225 offset:19456
	ds_read_b128 v[176:179], v225 offset:20480
	ds_read_b128 v[180:183], v225 offset:21504
	ds_read_b128 v[204:207], v225 offset:22528
	ds_read_b128 v[208:211], v225 offset:23552
	global_load_lds_dwordx4 v[212:213], off
	s_add_i32 m0, s69, 0x2000
	s_add_u32 s70, s20, 0x50000
	v_lshl_add_u64 v[214:215], s[20:21], 0, v[194:195]
	s_addc_u32 s71, s21, 0
	s_add_i32 s69, s45, s29
	global_load_lds_dwordx4 v[214:215], off
	v_lshl_add_u64 v[216:217], s[70:71], 0, v[190:191]
	s_mov_b32 m0, s69
	v_lshl_add_u64 v[218:219], s[22:23], 0, v[192:193]
	global_load_lds_dwordx4 v[216:217], off
	v_lshl_add_u64 v[216:217], s[70:71], 0, v[194:195]
	s_add_i32 m0, s69, 0x2000
	s_nop 0
	global_load_lds_dwordx4 v[216:217], off
	v_lshl_add_u64 v[216:217], s[22:23], 0, v[188:189]
	s_mov_b32 m0, s30
	s_nop 0
	global_load_lds_dwordx4 v[216:217], off
	s_mov_b32 m0, s31
	s_nop 0
	global_load_lds_dwordx4 v[218:219], off
	s_waitcnt vmcnt(8)
	s_waitcnt lgkmcnt(0)
	s_barrier
; #define PG8_STAGE(bufoff, gbase, voff) do { _Pragma("unroll") for (int _i = 0; _i < 2; ++_i) \
;         __builtin_amdgcn_global_load_lds((const unsigned*)((const char*)(gbase) + (voff)[_i]), (PG8_LAS unsigned*)(lds + (bufoff) + ldsw + _i * 8192), 16, 0, 0); } while (0)
; #define PG8_LDA(dst, b, h) do { _Pragma("unroll") for (int m = 0; m < 4; ++m) _Pragma("unroll") for (int k = 0; k < 2; ++k) dst[m][k] = *(const PG8_LAS bf16x8*)(lds + PG8_SA(b, h) + aoff + m * 2048 + k * 1024); } while (0)
; #define PG8_LDB(dst, b, h) do { _Pragma("unroll") for (int n = 0; n < 2; ++n) _Pragma("unroll") for (int k = 0; k < 2; ++k) dst[n][k] = *(const PG8_LAS bf16x8*)(lds + PG8_SB(b, h) + boff + n * 2048 + k * 1024); } while (0)
; #define PG8_MMA(ai, bj, At, Bt) do { __builtin_amdgcn_s_setprio(1); _Pragma("unroll") for (int m = 0; m < 4; ++m) _Pragma("unroll") for (int n = 0; n < 2; ++n) _Pragma("unroll") for (int k = 0; k < 2; ++k) \
;         acc[ai][bj][m][n] = __builtin_amdgcn_mfma_f32_16x16x32_bf16(Bt[n][k], At[m][k], acc[ai][bj][m][n], 0, 0, 0); __builtin_amdgcn_s_setprio(0); } while (0)
; #define PG8_WAIT_V(n) asm volatile("s_waitcnt vmcnt(" #n ")" ::: "memory")
; #define PG8_WAIT_L(n) asm volatile("s_waitcnt lgkmcnt(" #n ")" ::: "memory")
; #define PG8_BAR __builtin_amdgcn_s_barrier()
; #define PG8_SCHED __builtin_amdgcn_sched_barrier(0)
; template <class Epi, class Sched, bool ALIGN_EPI = false, bool SP2 = false>
; __device__ __forceinline__ void gemm_phase(PG8_LAS unsigned char* lds, const Gemm g, const Sched& S, const Epi& E) {
;     ...
;             PG8_WAIT_V(8); PG8_WAIT_L(0); PG8_BAR; PG8_MMA(1, 0, At, B0); PG8_MMA(1, 1, At, B1); PG8_BAR; PG8_SCHED;
;             PG8_LDB(B0, 1, 0); PG8_LDB(B1, 1, 1); PG8_SCHED; PG8_LDA(At, 1, 0); PG8_STAGE(PG8_SA(0, 1), a2 + hstep, voffA);
;             PG8_WAIT_V(8); PG8_WAIT_L(0); PG8_BAR; PG8_MMA(0, 0, At, B0); PG8_MMA(0, 1, At, B1); PG8_BAR; PG8_SCHED;
	s_setprio 1
	s_waitcnt lgkmcnt(0)
	v_mfma_f32_16x16x32_bf16 v[60:63], v[100:103], v[160:163], v[60:63]
	v_mfma_f32_16x16x32_bf16 v[56:59], v[120:123], v[160:163], v[56:59]
	v_mfma_f32_16x16x32_bf16 v[44:47], v[100:103], v[168:171], v[44:47]
	v_mfma_f32_16x16x32_bf16 v[40:43], v[120:123], v[168:171], v[40:43]
	v_mfma_f32_16x16x32_bf16 v[28:31], v[100:103], v[176:179], v[28:31]
	v_mfma_f32_16x16x32_bf16 v[24:27], v[120:123], v[176:179], v[24:27]
	v_mfma_f32_16x16x32_bf16 v[12:15], v[100:103], v[204:207], v[12:15]
	v_mfma_f32_16x16x32_bf16 v[8:11], v[120:123], v[204:207], v[8:11]
	v_mfma_f32_16x16x32_bf16 v[60:63], v[108:111], v[164:167], v[60:63]
	v_mfma_f32_16x16x32_bf16 v[56:59], v[132:135], v[164:167], v[56:59]
	v_mfma_f32_16x16x32_bf16 v[44:47], v[108:111], v[172:175], v[44:47]
	v_mfma_f32_16x16x32_bf16 v[40:43], v[132:135], v[172:175], v[40:43]
	v_mfma_f32_16x16x32_bf16 v[28:31], v[108:111], v[180:183], v[28:31]
	v_mfma_f32_16x16x32_bf16 v[24:27], v[132:135], v[180:183], v[24:27]
	v_mfma_f32_16x16x32_bf16 v[12:15], v[108:111], v[208:211], v[12:15]
	v_mfma_f32_16x16x32_bf16 v[8:11], v[132:135], v[208:211], v[8:11]
	s_setprio 0
	s_setprio 1
	v_mfma_f32_16x16x32_bf16 v[52:55], v[144:147], v[160:163], v[52:55]
	v_mfma_f32_16x16x32_bf16 v[48:51], v[152:155], v[160:163], v[48:51]
	v_mfma_f32_16x16x32_bf16 v[36:39], v[144:147], v[168:171], v[36:39]
	v_mfma_f32_16x16x32_bf16 v[32:35], v[152:155], v[168:171], v[32:35]
	v_mfma_f32_16x16x32_bf16 v[20:23], v[144:147], v[176:179], v[20:23]
	v_mfma_f32_16x16x32_bf16 v[16:19], v[152:155], v[176:179], v[16:19]
	v_mfma_f32_16x16x32_bf16 v[4:7], v[144:147], v[204:207], v[4:7]
	v_mfma_f32_16x16x32_bf16 v[0:3], v[152:155], v[204:207], v[0:3]
	v_mfma_f32_16x16x32_bf16 v[52:55], v[148:151], v[164:167], v[52:55]
	v_mfma_f32_16x16x32_bf16 v[48:51], v[156:159], v[164:167], v[48:51]
	v_mfma_f32_16x16x32_bf16 v[36:39], v[148:151], v[172:175], v[36:39]
	v_mfma_f32_16x16x32_bf16 v[32:35], v[156:159], v[172:175], v[32:35]
	v_mfma_f32_16x16x32_bf16 v[20:23], v[148:151], v[180:183], v[20:23]
	v_mfma_f32_16x16x32_bf16 v[16:19], v[156:159], v[180:183], v[16:19]
	v_mfma_f32_16x16x32_bf16 v[4:7], v[148:151], v[208:211], v[4:7]
	v_mfma_f32_16x16x32_bf16 v[0:3], v[156:159], v[208:211], v[0:3]
	s_setprio 0
	s_barrier
	s_add_i32 s69, 0, 0x18000
	s_add_i32 s70, 0, 0x1c000
	v_add_u32_e32 v132, s69, v187
	v_add_u32_e32 v156, s70, v187
	ds_read_b128 v[100:103], v132
	ds_read_b128 v[108:111], v132 offset:1024
	ds_read_b128 v[120:123], v132 offset:2048
	ds_read_b128 v[132:135], v132 offset:3072
	ds_read_b128 v[144:147], v156
	ds_read_b128 v[148:151], v156 offset:1024
	ds_read_b128 v[152:155], v156 offset:2048
	ds_read_b128 v[156:159], v156 offset:3072
	s_add_u32 s22, s22, 0x50000
	s_addc_u32 s23, s23, 0
	s_mov_b32 m0, s34
	v_lshl_add_u64 v[220:221], s[22:23], 0, v[188:189]
	ds_read_b128 v[160:163], v225 offset:32768
	ds_read_b128 v[164:167], v225 offset:33792
	ds_read_b128 v[168:171], v225 offset:34816
	ds_read_b128 v[172:175], v225 offset:35840
	ds_read_b128 v[176:179], v225 offset:36864
	ds_read_b128 v[180:183], v225 offset:37888
	ds_read_b128 v[204:207], v225 offset:38912
	ds_read_b128 v[208:211], v225 offset:39936
	global_load_lds_dwordx4 v[220:221], off
	v_lshl_add_u64 v[220:221], s[22:23], 0, v[192:193]
	s_mov_b32 m0, s35
	s_nop 0
	global_load_lds_dwordx4 v[220:221], off
	s_waitcnt vmcnt(8)
	s_waitcnt lgkmcnt(0)
	s_barrier
	s_setprio 1
	s_waitcnt lgkmcnt(0)
	v_mfma_f32_16x16x32_bf16 v[140:143], v[100:103], v[160:163], v[140:143]
	v_mfma_f32_16x16x32_bf16 v[136:139], v[120:123], v[160:163], v[136:139]
	v_mfma_f32_16x16x32_bf16 v[116:119], v[100:103], v[168:171], v[116:119]
	v_mfma_f32_16x16x32_bf16 v[112:115], v[120:123], v[168:171], v[112:115]
	v_mfma_f32_16x16x32_bf16 v[92:95], v[100:103], v[176:179], v[92:95]
	v_mfma_f32_16x16x32_bf16 v[88:91], v[120:123], v[176:179], v[88:91]
	v_mfma_f32_16x16x32_bf16 v[76:79], v[100:103], v[204:207], v[76:79]
	v_mfma_f32_16x16x32_bf16 v[72:75], v[120:123], v[204:207], v[72:75]
	v_mfma_f32_16x16x32_bf16 v[140:143], v[108:111], v[164:167], v[140:143]
	v_mfma_f32_16x16x32_bf16 v[136:139], v[132:135], v[164:167], v[136:139]
	v_mfma_f32_16x16x32_bf16 v[116:119], v[108:111], v[172:175], v[116:119]
	v_mfma_f32_16x16x32_bf16 v[112:115], v[132:135], v[172:175], v[112:115]
	v_mfma_f32_16x16x32_bf16 v[92:95], v[108:111], v[180:183], v[92:95]
	v_mfma_f32_16x16x32_bf16 v[88:91], v[132:135], v[180:183], v[88:91]
	v_mfma_f32_16x16x32_bf16 v[76:79], v[108:111], v[208:211], v[76:79]
	v_mfma_f32_16x16x32_bf16 v[72:75], v[132:135], v[208:211], v[72:75]
	s_setprio 0
	s_setprio 1
	v_mfma_f32_16x16x32_bf16 v[128:131], v[144:147], v[160:163], v[128:131]
	v_mfma_f32_16x16x32_bf16 v[124:127], v[152:155], v[160:163], v[124:127]
	v_mfma_f32_16x16x32_bf16 v[104:107], v[144:147], v[168:171], v[104:107]
	v_mfma_f32_16x16x32_bf16 v[96:99], v[152:155], v[168:171], v[96:99]
	v_mfma_f32_16x16x32_bf16 v[84:87], v[144:147], v[176:179], v[84:87]
	v_mfma_f32_16x16x32_bf16 v[80:83], v[152:155], v[176:179], v[80:83]
	v_mfma_f32_16x16x32_bf16 v[68:71], v[144:147], v[204:207], v[68:71]
	v_mfma_f32_16x16x32_bf16 v[64:67], v[152:155], v[204:207], v[64:67]
	v_mfma_f32_16x16x32_bf16 v[128:131], v[148:151], v[164:167], v[128:131]
	v_mfma_f32_16x16x32_bf16 v[124:127], v[156:159], v[164:167], v[124:127]
	v_mfma_f32_16x16x32_bf16 v[104:107], v[148:151], v[172:175], v[104:107]
	v_mfma_f32_16x16x32_bf16 v[96:99], v[156:159], v[172:175], v[96:99]
	v_mfma_f32_16x16x32_bf16 v[84:87], v[148:151], v[180:183], v[84:87]
	v_mfma_f32_16x16x32_bf16 v[80:83], v[156:159], v[180:183], v[80:83]
	v_mfma_f32_16x16x32_bf16 v[68:71], v[148:151], v[208:211], v[68:71]
	v_mfma_f32_16x16x32_bf16 v[64:67], v[156:159], v[208:211], v[64:67]
	s_setprio 0
	s_barrier
; __device__ __forceinline__ unsigned cvt_pk_bf16(float lo, float hi) { unsigned r; asm volatile("v_cvt_pk_bf16_f32 %0, %1, %2" : "=v"(r) : "v"(lo), "v"(hi)); return r; }
; #define PG8_STAGE(bufoff, gbase, voff) do { _Pragma("unroll") for (int _i = 0; _i < 2; ++_i) \
;         __builtin_amdgcn_global_load_lds((const unsigned*)((const char*)(gbase) + (voff)[_i]), (PG8_LAS unsigned*)(lds + (bufoff) + ldsw + _i * 8192), 16, 0, 0); } while (0)
; #define PG8_WAIT_V(n) asm volatile("s_waitcnt vmcnt(" #n ")" ::: "memory")
;     __device__ __forceinline__ void operator()(const f32x4 (&acc)[2][2][4][2], const Unit& u, int wr, int wc, int fr, int fq) const {
;     ...
;                 for (int bj = 0; bj < 2; ++bj) rb[ai][m][bj] = *(const u32x4*)(base + (size_t)(row0 + ai * HALF + m * 16) * ldc + col0 + bj * HALF);
;         asm volatile("" ::: "memory");
; #pragma unroll
;         for (int ai = 0; ai < 2; ++ai)
; #pragma unroll
;             for (int m = 0; m < 4; ++m) { const int row = row0 + ai * HALF + m * 16; float s = 0.f;
; #pragma unroll
;                 for (int bj = 0; bj < 2; ++bj) { const u32x4 w = rb[ai][m][bj];
;                     const f32x4 v0 = acc[ai][bj][m][0] + (f32x4){__uint_as_float(w.x << 16), __uint_as_float(w.x & 0xffff0000u), __uint_as_float(w.y << 16), __uint_as_float(w.y & 0xffff0000u)};
;                     const f32x4 v1 = acc[ai][bj][m][1] + (f32x4){__uint_as_float(w.z << 16), __uint_as_float(w.z & 0xffff0000u), __uint_as_float(w.w << 16), __uint_as_float(w.w & 0xffff0000u)};
;                     s += ((v0[0] * v0[0] + v0[1] * v0[1]) + (v0[2] * v0[2] + v0[3] * v0[3])) + ((v1[0] * v1[0] + v1[1] * v1[1]) + (v1[2] * v1[2] + v1[3] * v1[3]));
;                     u32x4 o; o.x = cvt_pk_bf16(v0[0], v0[1]); o.y = cvt_pk_bf16(v0[2], v0[3]); o.z = cvt_pk_bf16(v1[0], v1[1]); o.w = cvt_pk_bf16(v1[2], v1[3]);
;                     *(u32x4*)(outb + (size_t)row * ldc + col0 + bj * HALF) = o; }
; template <class Epi, class Sched, bool ALIGN_EPI = false, bool SP2 = false>
; __device__ __forceinline__ void gemm_phase(PG8_LAS unsigned char* lds, const Gemm g, const Sched& S, const Epi& E) {
;     ...
;             PG8_LDA(At, 1, 1); PG8_STAGE(PG8_SB(1, 0), b3, voffB); PG8_STAGE(PG8_SB(1, 1), b3 + hstep, voffB); PG8_STAGE(PG8_SA(1, 0), a3, voffA);
;             PG8_WAIT_V(8); PG8_WAIT_L(0); PG8_BAR; PG8_MMA(1, 0, At, B0); PG8_MMA(1, 1, At, B1); PG8_BAR; PG8_SCHED;
	s_add_i32 s22, s69, s29
	v_lshl_add_u64 v[212:213], v[212:213], 0, s[16:17]
	s_mov_b32 m0, s22
	ds_read_b128 v[160:163], v225 offset:49152
	ds_read_b128 v[164:167], v225 offset:50176
	ds_read_b128 v[168:171], v225 offset:51200
	ds_read_b128 v[172:175], v225 offset:52224
	ds_read_b128 v[176:179], v225 offset:53248
	ds_read_b128 v[180:183], v225 offset:54272
	ds_read_b128 v[204:207], v225 offset:55296
	ds_read_b128 v[208:211], v225 offset:56320
	global_load_lds_dwordx4 v[212:213], off
	s_add_i32 m0, s22, 0x2000
	s_add_u32 s20, s20, 0x50080
	v_lshl_add_u64 v[212:213], v[214:215], 0, s[16:17]
	s_addc_u32 s21, s21, 0
	s_add_i32 s22, s70, s29
	global_load_lds_dwordx4 v[212:213], off
	v_lshl_add_u64 v[212:213], s[20:21], 0, v[190:191]
	s_mov_b32 m0, s22
	s_nop 0
	global_load_lds_dwordx4 v[212:213], off
	v_lshl_add_u64 v[212:213], s[20:21], 0, v[194:195]
	s_add_i32 m0, s22, 0x2000
	s_nop 0
	global_load_lds_dwordx4 v[212:213], off
	v_lshl_add_u64 v[212:213], v[216:217], 0, s[16:17]
	s_mov_b32 m0, s37
	s_nop 0
	global_load_lds_dwordx4 v[212:213], off
	v_lshl_add_u64 v[212:213], v[218:219], 0, s[16:17]
	s_mov_b32 m0, s38
	s_nop 0
	global_load_lds_dwordx4 v[212:213], off
	s_waitcnt vmcnt(8)
	s_waitcnt lgkmcnt(0)
	s_barrier
	s_setprio 1
	s_waitcnt lgkmcnt(0)
	v_mfma_f32_16x16x32_bf16 v[60:63], v[100:103], v[160:163], v[60:63]
	v_mfma_f32_16x16x32_bf16 v[56:59], v[120:123], v[160:163], v[56:59]
	v_mfma_f32_16x16x32_bf16 v[44:47], v[100:103], v[168:171], v[44:47]
	v_mfma_f32_16x16x32_bf16 v[40:43], v[120:123], v[168:171], v[40:43]
	v_mfma_f32_16x16x32_bf16 v[28:31], v[100:103], v[176:179], v[28:31]
	v_mfma_f32_16x16x32_bf16 v[24:27], v[120:123], v[176:179], v[24:27]
	v_mfma_f32_16x16x32_bf16 v[12:15], v[100:103], v[204:207], v[12:15]
	v_mfma_f32_16x16x32_bf16 v[8:11], v[120:123], v[204:207], v[8:11]
	v_mfma_f32_16x16x32_bf16 v[60:63], v[108:111], v[164:167], v[60:63]
	v_mfma_f32_16x16x32_bf16 v[56:59], v[132:135], v[164:167], v[56:59]
	v_mfma_f32_16x16x32_bf16 v[44:47], v[108:111], v[172:175], v[44:47]
	v_mfma_f32_16x16x32_bf16 v[40:43], v[132:135], v[172:175], v[40:43]
	v_mfma_f32_16x16x32_bf16 v[28:31], v[108:111], v[180:183], v[28:31]
	v_mfma_f32_16x16x32_bf16 v[24:27], v[132:135], v[180:183], v[24:27]
	v_mfma_f32_16x16x32_bf16 v[12:15], v[108:111], v[208:211], v[12:15]
	v_mfma_f32_16x16x32_bf16 v[8:11], v[132:135], v[208:211], v[8:11]
	s_setprio 0
	s_setprio 1
	v_mfma_f32_16x16x32_bf16 v[52:55], v[144:147], v[160:163], v[52:55]
	v_mfma_f32_16x16x32_bf16 v[48:51], v[152:155], v[160:163], v[48:51]
	v_mfma_f32_16x16x32_bf16 v[36:39], v[144:147], v[168:171], v[36:39]
	v_mfma_f32_16x16x32_bf16 v[32:35], v[152:155], v[168:171], v[32:35]
	v_mfma_f32_16x16x32_bf16 v[20:23], v[144:147], v[176:179], v[20:23]
	v_mfma_f32_16x16x32_bf16 v[16:19], v[152:155], v[176:179], v[16:19]
	v_mfma_f32_16x16x32_bf16 v[4:7], v[144:147], v[204:207], v[4:7]
	v_mfma_f32_16x16x32_bf16 v[0:3], v[152:155], v[204:207], v[0:3]
	v_mfma_f32_16x16x32_bf16 v[52:55], v[148:151], v[164:167], v[52:55]
	v_mfma_f32_16x16x32_bf16 v[48:51], v[156:159], v[164:167], v[48:51]
	v_mfma_f32_16x16x32_bf16 v[36:39], v[148:151], v[172:175], v[36:39]
	v_mfma_f32_16x16x32_bf16 v[32:35], v[156:159], v[172:175], v[32:35]
	v_mfma_f32_16x16x32_bf16 v[20:23], v[148:151], v[180:183], v[20:23]
	v_mfma_f32_16x16x32_bf16 v[16:19], v[156:159], v[180:183], v[16:19]
	v_mfma_f32_16x16x32_bf16 v[4:7], v[148:151], v[208:211], v[4:7]
	v_mfma_f32_16x16x32_bf16 v[0:3], v[156:159], v[208:211], v[0:3]
	s_setprio 0
	s_barrier
	s_add_i32 s58, s58, 2
	s_add_u32 s18, s18, 0x100
	s_addc_u32 s19, s19, 0
	s_add_u32 s50, s50, 0x100
	s_addc_u32 s51, s51, 0
	s_cmp_gt_u32 s58, 17
	s_cbranch_scc0 .LBB0_404
	v_lshl_or_b32 v204, s48, 8, v222
	v_lshl_add_u32 v220, s49, 8, v185
	v_ashrrev_i32_e32 v205, 31, v204
	v_lshlrev_b64 v[238:239], 1, v[204:205]
	v_ashrrev_i32_e32 v221, 31, v220
	v_lshl_add_u64 v[100:101], s[12:13], 0, v[238:239]
	v_lshlrev_b64 v[240:241], 11, v[220:221]
	v_lshl_add_u64 v[102:103], v[100:101], 0, v[240:241]
	v_or_b32_e32 v218, 16, v220
	v_or_b32_e32 v216, 32, v220
	v_or_b32_e32 v214, 48, v220
	v_add_u32_e32 v212, 0x80, v220
	v_add_u32_e32 v210, 0x90, v220
	v_add_u32_e32 v208, 0xa0, v220
	v_add_u32_e32 v206, 0xb0, v220
	v_ashrrev_i32_e32 v219, 31, v218
	v_ashrrev_i32_e32 v217, 31, v216
	v_ashrrev_i32_e32 v215, 31, v214
	v_ashrrev_i32_e32 v213, 31, v212
	v_ashrrev_i32_e32 v211, 31, v210
	v_ashrrev_i32_e32 v209, 31, v208
	v_ashrrev_i32_e32 v207, 31, v206
	v_lshlrev_b64 v[102:103], 11, v[218:219]
	v_lshlrev_b64 v[108:109], 11, v[216:217]
	v_lshlrev_b64 v[110:111], 11, v[214:215]
	v_lshlrev_b64 v[120:121], 11, v[212:213]
	v_lshlrev_b64 v[122:123], 11, v[210:211]
	v_lshlrev_b64 v[132:133], 11, v[208:209]
	v_lshlrev_b64 v[134:135], 11, v[206:207]
	v_lshl_add_u64 v[102:103], v[100:101], 0, v[102:103]
	v_lshl_add_u64 v[108:109], v[100:101], 0, v[108:109]
	v_lshl_add_u64 v[110:111], v[100:101], 0, v[110:111]
	v_lshl_add_u64 v[120:121], v[100:101], 0, v[120:121]
	v_lshl_add_u64 v[122:123], v[100:101], 0, v[122:123]
	v_lshl_add_u64 v[242:243], v[100:101], 0, v[132:133]
	v_lshl_add_u64 v[100:101], v[100:101], 0, v[134:135]
	s_nop 0
	s_nop 0
	v_mul_f32_e32 v227, v141, v141
	v_mul_f32_e32 v233, v143, v143
	v_mul_f32_e32 v234, v137, v137
	v_mul_f32_e32 v235, v139, v139
	v_fmac_f32_e32 v227, v140, v140
	v_fmac_f32_e32 v233, v142, v142
	v_fmac_f32_e32 v234, v136, v136
	v_fmac_f32_e32 v235, v138, v138
	v_mov_b32_e32 v228, v128
	v_mov_b32_e32 v229, v129
	v_mov_b32_e32 v230, v126
	v_mov_b32_e32 v231, v127
	v_cvt_pk_bf16_f32 v126, v140, v141
	v_cvt_pk_bf16_f32 v127, v142, v143
	v_cvt_pk_bf16_f32 v128, v136, v137
	v_add_f32_e32 v136, v227, v233
	v_add_f32_e32 v137, v234, v235
	v_cvt_pk_bf16_f32 v129, v138, v139
	v_add_f32_e32 v138, v136, v137
	v_mov_b32_e32 v136, v124
	v_mov_b32_e32 v137, v125
	v_mul_f32_e32 v124, v229, v229
	v_mul_f32_e32 v125, v131, v131
	v_fmac_f32_e32 v124, v228, v228
	v_fmac_f32_e32 v125, v130, v130
	v_add_f32_e32 v124, v124, v125
	v_mul_f32_e32 v125, v137, v137
	v_mul_f32_e32 v139, v231, v231
	v_fmac_f32_e32 v125, v136, v136
	v_fmac_f32_e32 v139, v230, v230
	v_add_f32_e32 v125, v125, v139
	v_add_f32_e32 v124, v124, v125
	v_add_f32_e32 v125, v138, v124
	v_and_b32_e32 v138, 64, v226
	v_xor_b32_e32 v124, 16, v226
	v_add_u32_e32 v140, 64, v138
	v_cmp_lt_i32_e32 vcc, v124, v140
	v_lshl_add_u64 v[138:139], s[12:13], 0, v[240:241]
	v_lshl_add_u64 v[138:139], v[138:139], 0, v[238:239]
	v_cndmask_b32_e32 v124, v226, v124, vcc
	v_lshlrev_b32_e32 v124, 2, v124
	ds_bpermute_b32 v141, v124, v125
	global_store_dwordx4 v[138:139], v[126:129], off
	s_nop 1
	v_cvt_pk_bf16_f32 v128, v228, v229
	s_waitcnt lgkmcnt(0)
; __device__ __forceinline__ unsigned cvt_pk_bf16(float lo, float hi) { unsigned r; asm volatile("v_cvt_pk_bf16_f32 %0, %1, %2" : "=v"(r) : "v"(lo), "v"(hi)); return r; }
;     __device__ __forceinline__ void operator()(const f32x4 (&acc)[2][2][4][2], const Unit& u, int wr, int wc, int fr, int fq) const {
;     ...
;             for (int m = 0; m < 4; ++m) { const int row = row0 + ai * HALF + m * 16; float s = 0.f;
; #pragma unroll
;                 for (int bj = 0; bj < 2; ++bj) { const u32x4 w = rb[ai][m][bj];
;                     const f32x4 v0 = acc[ai][bj][m][0] + (f32x4){__uint_as_float(w.x << 16), __uint_as_float(w.x & 0xffff0000u), __uint_as_float(w.y << 16), __uint_as_float(w.y & 0xffff0000u)};
;                     const f32x4 v1 = acc[ai][bj][m][1] + (f32x4){__uint_as_float(w.z << 16), __uint_as_float(w.z & 0xffff0000u), __uint_as_float(w.w << 16), __uint_as_float(w.w & 0xffff0000u)};
;                     s += ((v0[0] * v0[0] + v0[1] * v0[1]) + (v0[2] * v0[2] + v0[3] * v0[3])) + ((v1[0] * v1[0] + v1[1] * v1[1]) + (v1[2] * v1[2] + v1[3] * v1[3]));
;                     u32x4 o; o.x = cvt_pk_bf16(v0[0], v0[1]); o.y = cvt_pk_bf16(v0[2], v0[3]); o.z = cvt_pk_bf16(v1[0], v1[1]); o.w = cvt_pk_bf16(v1[2], v1[3]);
;                     *(u32x4*)(outb + (size_t)row * ldc + col0 + bj * HALF) = o; }
;                 s += __shfl_xor(s, 16); s += __shfl_xor(s, 32);
;                 if (fq == 0) atomicAdd(ssq + row, s); }
	v_add_f32_e32 v126, v125, v141
	v_xor_b32_e32 v125, 32, v226
	v_cmp_lt_i32_e32 vcc, v125, v140
	v_cvt_pk_bf16_f32 v129, v130, v131
	v_cvt_pk_bf16_f32 v130, v136, v137
	v_cvt_pk_bf16_f32 v131, v230, v231
	global_store_dwordx4 v[138:139], v[128:131], off offset:256
	s_nop 0
	v_cndmask_b32_e32 v125, v226, v125, vcc
	v_lshlrev_b32_e32 v125, 2, v125
	ds_bpermute_b32 v127, v125, v126
	s_and_saveexec_b64 s[18:19], s[2:3]
	s_cbranch_execz .LBB0_407
	v_lshl_add_u64 v[128:129], v[220:221], 2, s[14:15]
	s_waitcnt lgkmcnt(0)
	v_add_f32_e32 v126, v126, v127
	global_atomic_add_f32 v[128:129], v126, off
.LBB0_407:
	s_or_b64 exec, exec, s[18:19]
	v_mov_b32_e32 v130, v114
	v_mov_b32_e32 v131, v115
	v_mov_b32_e32 v114, v112
	v_mov_b32_e32 v115, v113
	v_mul_f32_e32 v112, v117, v117
	v_mul_f32_e32 v113, v119, v119
	v_fmac_f32_e32 v112, v116, v116
	v_fmac_f32_e32 v113, v118, v118
	v_add_f32_e32 v112, v112, v113
	v_mul_f32_e32 v113, v115, v115
	v_mul_f32_e32 v128, v131, v131
	v_fmac_f32_e32 v113, v114, v114
	v_fmac_f32_e32 v128, v130, v130
	v_add_f32_e32 v113, v113, v128
	v_add_f32_e32 v128, v112, v113
	v_cvt_pk_bf16_f32 v112, v116, v117
	v_cvt_pk_bf16_f32 v113, v118, v119
	v_mov_b32_e32 v116, v96
	v_mov_b32_e32 v117, v97
	v_mul_f32_e32 v96, v105, v105
	v_mul_f32_e32 v97, v107, v107
	v_fmac_f32_e32 v96, v104, v104
	v_fmac_f32_e32 v97, v106, v106
	v_add_f32_e32 v96, v96, v97
	v_mul_f32_e32 v97, v117, v117
	v_mul_f32_e32 v118, v99, v99
	v_fmac_f32_e32 v97, v116, v116
	v_fmac_f32_e32 v118, v98, v98
	v_add_f32_e32 v97, v97, v118
	v_add_f32_e32 v96, v96, v97
	v_add_f32_e32 v128, v128, v96
	ds_bpermute_b32 v129, v124, v128
	s_waitcnt lgkmcnt(1)
	v_lshlrev_b64 v[126:127], 10, v[218:219]
	v_lshl_add_u64 v[96:97], v[126:127], 1, s[12:13]
	v_lshl_add_u64 v[118:119], v[204:205], 1, v[96:97]
	v_cvt_pk_bf16_f32 v114, v114, v115
	s_waitcnt lgkmcnt(0)
	v_add_f32_e32 v96, v128, v129
	ds_bpermute_b32 v97, v125, v96
	v_cvt_pk_bf16_f32 v115, v130, v131
	global_store_dwordx4 v[118:119], v[112:115], off
	v_cvt_pk_bf16_f32 v104, v104, v105
	v_cvt_pk_bf16_f32 v105, v106, v107
	v_cvt_pk_bf16_f32 v106, v116, v117
	v_cvt_pk_bf16_f32 v107, v98, v99
	global_store_dwordx4 v[118:119], v[104:107], off offset:256
	s_and_saveexec_b64 s[18:19], s[2:3]
	s_cbranch_execz .LBB0_409
	v_lshl_add_u64 v[98:99], v[218:219], 2, s[14:15]
	s_waitcnt lgkmcnt(0)
	v_add_f32_e32 v96, v96, v97
	global_atomic_add_f32 v[98:99], v96, off
.LBB0_409:
	s_or_b64 exec, exec, s[18:19]
	v_mov_b32_e32 v104, v90
	v_mov_b32_e32 v105, v91
	v_mov_b32_e32 v90, v88
	v_mov_b32_e32 v91, v89
	v_mul_f32_e32 v88, v93, v93
	v_mul_f32_e32 v89, v95, v95
	v_fmac_f32_e32 v88, v92, v92
	v_fmac_f32_e32 v89, v94, v94
	v_add_f32_e32 v88, v88, v89
	v_mul_f32_e32 v89, v91, v91
	v_mul_f32_e32 v98, v105, v105
	v_fmac_f32_e32 v89, v90, v90
	v_fmac_f32_e32 v98, v104, v104
	v_add_f32_e32 v89, v89, v98
	v_add_f32_e32 v98, v88, v89
	v_cvt_pk_bf16_f32 v88, v92, v93
	v_cvt_pk_bf16_f32 v89, v94, v95
	v_mov_b32_e32 v92, v80
	v_mov_b32_e32 v93, v81
	v_mul_f32_e32 v80, v85, v85
	v_mul_f32_e32 v81, v87, v87
	v_mov_b32_e32 v94, v82
	v_mov_b32_e32 v95, v83
	v_fmac_f32_e32 v80, v84, v84
	v_fmac_f32_e32 v81, v86, v86
	v_add_f32_e32 v80, v80, v81
	v_mul_f32_e32 v81, v93, v93
	v_mul_f32_e32 v82, v95, v95
	v_fmac_f32_e32 v81, v92, v92
	v_fmac_f32_e32 v82, v94, v94
	v_add_f32_e32 v81, v81, v82
	v_add_f32_e32 v80, v80, v81
	v_add_f32_e32 v83, v98, v80
	ds_bpermute_b32 v98, v124, v83
	s_waitcnt lgkmcnt(1)
	v_lshlrev_b64 v[96:97], 10, v[216:217]
	v_lshl_add_u64 v[80:81], v[96:97], 1, s[12:13]
	v_lshl_add_u64 v[96:97], v[204:205], 1, v[80:81]
	v_cvt_pk_bf16_f32 v90, v90, v91
	s_waitcnt lgkmcnt(0)
	v_add_f32_e32 v80, v83, v98
	ds_bpermute_b32 v81, v125, v80
	v_cvt_pk_bf16_f32 v91, v104, v105
	global_store_dwordx4 v[96:97], v[88:91], off
	v_cvt_pk_bf16_f32 v82, v84, v85
	v_cvt_pk_bf16_f32 v83, v86, v87
	v_cvt_pk_bf16_f32 v84, v92, v93
	v_cvt_pk_bf16_f32 v85, v94, v95
	global_store_dwordx4 v[96:97], v[82:85], off offset:256
	s_and_saveexec_b64 s[18:19], s[2:3]
	s_cbranch_execz .LBB0_411
	v_lshl_add_u64 v[82:83], v[216:217], 2, s[14:15]
	s_waitcnt lgkmcnt(0)
	v_add_f32_e32 v80, v80, v81
	global_atomic_add_f32 v[82:83], v80, off
.LBB0_411:
	s_or_b64 exec, exec, s[18:19]
	v_mov_b32_e32 v84, v74
	v_mov_b32_e32 v85, v75
	v_mov_b32_e32 v74, v72
	v_mov_b32_e32 v75, v73
	v_mul_f32_e32 v72, v77, v77
	v_mul_f32_e32 v73, v79, v79
	v_fmac_f32_e32 v72, v76, v76
	v_fmac_f32_e32 v73, v78, v78
	v_add_f32_e32 v72, v72, v73
	v_mul_f32_e32 v73, v75, v75
	v_mul_f32_e32 v82, v85, v85
	v_fmac_f32_e32 v73, v74, v74
	v_fmac_f32_e32 v82, v84, v84
	v_add_f32_e32 v73, v73, v82
	v_add_f32_e32 v82, v72, v73
	v_cvt_pk_bf16_f32 v72, v76, v77
	v_cvt_pk_bf16_f32 v73, v78, v79
	v_mov_b32_e32 v76, v64
	v_mov_b32_e32 v77, v65
	v_mul_f32_e32 v64, v69, v69
	v_mul_f32_e32 v65, v71, v71
	v_mov_b32_e32 v78, v66
	v_mov_b32_e32 v79, v67
	v_fmac_f32_e32 v64, v68, v68
	v_fmac_f32_e32 v65, v70, v70
	v_add_f32_e32 v64, v64, v65
	v_mul_f32_e32 v65, v77, v77
	v_mul_f32_e32 v66, v79, v79
	v_fmac_f32_e32 v65, v76, v76
	v_fmac_f32_e32 v66, v78, v78
	v_add_f32_e32 v65, v65, v66
	v_add_f32_e32 v64, v64, v65
	v_add_f32_e32 v67, v82, v64
	ds_bpermute_b32 v82, v124, v67
	s_waitcnt lgkmcnt(1)
	v_lshlrev_b64 v[80:81], 10, v[214:215]
	v_lshl_add_u64 v[64:65], v[80:81], 1, s[12:13]
	v_lshl_add_u64 v[80:81], v[204:205], 1, v[64:65]
	v_cvt_pk_bf16_f32 v74, v74, v75
	s_waitcnt lgkmcnt(0)
	v_add_f32_e32 v64, v67, v82
	ds_bpermute_b32 v65, v125, v64
	v_cvt_pk_bf16_f32 v75, v84, v85
	global_store_dwordx4 v[80:81], v[72:75], off
	v_cvt_pk_bf16_f32 v66, v68, v69
	v_cvt_pk_bf16_f32 v67, v70, v71
	v_cvt_pk_bf16_f32 v68, v76, v77
	v_cvt_pk_bf16_f32 v69, v78, v79
	global_store_dwordx4 v[80:81], v[66:69], off offset:256
	s_and_saveexec_b64 s[18:19], s[2:3]
	s_cbranch_execz .LBB0_413
	v_lshl_add_u64 v[66:67], v[214:215], 2, s[14:15]
	s_waitcnt lgkmcnt(0)
	v_add_f32_e32 v64, v64, v65
	global_atomic_add_f32 v[66:67], v64, off
; __device__ __forceinline__ unsigned cvt_pk_bf16(float lo, float hi) { unsigned r; asm volatile("v_cvt_pk_bf16_f32 %0, %1, %2" : "=v"(r) : "v"(lo), "v"(hi)); return r; }
;     __device__ __forceinline__ void operator()(const f32x4 (&acc)[2][2][4][2], const Unit& u, int wr, int wc, int fr, int fq) const {
;     ...
;             for (int m = 0; m < 4; ++m) { const int row = row0 + ai * HALF + m * 16; float s = 0.f;
; #pragma unroll
;                 for (int bj = 0; bj < 2; ++bj) { const u32x4 w = rb[ai][m][bj];
;                     const f32x4 v0 = acc[ai][bj][m][0] + (f32x4){__uint_as_float(w.x << 16), __uint_as_float(w.x & 0xffff0000u), __uint_as_float(w.y << 16), __uint_as_float(w.y & 0xffff0000u)};
;                     const f32x4 v1 = acc[ai][bj][m][1] + (f32x4){__uint_as_float(w.z << 16), __uint_as_float(w.z & 0xffff0000u), __uint_as_float(w.w << 16), __uint_as_float(w.w & 0xffff0000u)};
;                     s += ((v0[0] * v0[0] + v0[1] * v0[1]) + (v0[2] * v0[2] + v0[3] * v0[3])) + ((v1[0] * v1[0] + v1[1] * v1[1]) + (v1[2] * v1[2] + v1[3] * v1[3]));
;                     u32x4 o; o.x = cvt_pk_bf16(v0[0], v0[1]); o.y = cvt_pk_bf16(v0[2], v0[3]); o.z = cvt_pk_bf16(v1[0], v1[1]); o.w = cvt_pk_bf16(v1[2], v1[3]);
;                     *(u32x4*)(outb + (size_t)row * ldc + col0 + bj * HALF) = o; }
;                 s += __shfl_xor(s, 16); s += __shfl_xor(s, 32);
;                 if (fq == 0) atomicAdd(ssq + row, s); }
.LBB0_413:
	s_or_b64 exec, exec, s[18:19]
	v_mov_b32_e32 v68, v58
	v_mov_b32_e32 v69, v59
	v_mov_b32_e32 v58, v56
	v_mov_b32_e32 v59, v57
	v_mul_f32_e32 v56, v61, v61
	v_mul_f32_e32 v57, v63, v63
	v_fmac_f32_e32 v56, v60, v60
	v_fmac_f32_e32 v57, v62, v62
	v_add_f32_e32 v56, v56, v57
	v_mul_f32_e32 v57, v59, v59
	v_mul_f32_e32 v66, v69, v69
	v_fmac_f32_e32 v57, v58, v58
	v_fmac_f32_e32 v66, v68, v68
	v_add_f32_e32 v57, v57, v66
	v_add_f32_e32 v66, v56, v57
	v_cvt_pk_bf16_f32 v56, v60, v61
	v_cvt_pk_bf16_f32 v57, v62, v63
	v_mov_b32_e32 v60, v48
	v_mov_b32_e32 v61, v49
	v_mul_f32_e32 v48, v53, v53
	v_mul_f32_e32 v49, v55, v55
	v_mov_b32_e32 v62, v50
	v_mov_b32_e32 v63, v51
	v_fmac_f32_e32 v48, v52, v52
	v_fmac_f32_e32 v49, v54, v54
	v_add_f32_e32 v48, v48, v49
	v_mul_f32_e32 v49, v61, v61
	v_mul_f32_e32 v50, v63, v63
	v_fmac_f32_e32 v49, v60, v60
	v_fmac_f32_e32 v50, v62, v62
	v_add_f32_e32 v49, v49, v50
	v_add_f32_e32 v48, v48, v49
	v_add_f32_e32 v51, v66, v48
	ds_bpermute_b32 v66, v124, v51
	s_waitcnt lgkmcnt(1)
	v_lshlrev_b64 v[64:65], 10, v[212:213]
	v_lshl_add_u64 v[48:49], v[64:65], 1, s[12:13]
	v_lshl_add_u64 v[64:65], v[204:205], 1, v[48:49]
	v_cvt_pk_bf16_f32 v58, v58, v59
	s_waitcnt lgkmcnt(0)
	v_add_f32_e32 v48, v51, v66
	ds_bpermute_b32 v49, v125, v48
	v_cvt_pk_bf16_f32 v59, v68, v69
	global_store_dwordx4 v[64:65], v[56:59], off
	v_cvt_pk_bf16_f32 v50, v52, v53
	v_cvt_pk_bf16_f32 v51, v54, v55
	v_cvt_pk_bf16_f32 v52, v60, v61
	v_cvt_pk_bf16_f32 v53, v62, v63
	global_store_dwordx4 v[64:65], v[50:53], off offset:256
	s_and_saveexec_b64 s[18:19], s[2:3]
	s_cbranch_execz .LBB0_415
	v_lshl_add_u64 v[50:51], v[212:213], 2, s[14:15]
	s_waitcnt lgkmcnt(0)
	v_add_f32_e32 v48, v48, v49
	global_atomic_add_f32 v[50:51], v48, off
.LBB0_415:
	s_or_b64 exec, exec, s[18:19]
	v_mov_b32_e32 v52, v42
	v_mov_b32_e32 v53, v43
	v_mov_b32_e32 v42, v40
	v_mov_b32_e32 v43, v41
	v_mul_f32_e32 v40, v45, v45
	v_mul_f32_e32 v41, v47, v47
	v_fmac_f32_e32 v40, v44, v44
	v_fmac_f32_e32 v41, v46, v46
	v_add_f32_e32 v40, v40, v41
	v_mul_f32_e32 v41, v43, v43
	v_mul_f32_e32 v50, v53, v53
	v_fmac_f32_e32 v41, v42, v42
	v_fmac_f32_e32 v50, v52, v52
	v_add_f32_e32 v41, v41, v50
	v_add_f32_e32 v50, v40, v41
	v_cvt_pk_bf16_f32 v40, v44, v45
	v_cvt_pk_bf16_f32 v41, v46, v47
	v_mov_b32_e32 v44, v32
	v_mov_b32_e32 v45, v33
	v_mul_f32_e32 v32, v37, v37
	v_mul_f32_e32 v33, v39, v39
	v_mov_b32_e32 v46, v34
	v_mov_b32_e32 v47, v35
	v_fmac_f32_e32 v32, v36, v36
	v_fmac_f32_e32 v33, v38, v38
	v_add_f32_e32 v32, v32, v33
	v_mul_f32_e32 v33, v45, v45
	v_mul_f32_e32 v34, v47, v47
	v_fmac_f32_e32 v33, v44, v44
	v_fmac_f32_e32 v34, v46, v46
	v_add_f32_e32 v33, v33, v34
	v_add_f32_e32 v32, v32, v33
	v_add_f32_e32 v35, v50, v32
	ds_bpermute_b32 v50, v124, v35
	s_waitcnt lgkmcnt(1)
	v_lshlrev_b64 v[48:49], 10, v[210:211]
	v_lshl_add_u64 v[32:33], v[48:49], 1, s[12:13]
	v_lshl_add_u64 v[48:49], v[204:205], 1, v[32:33]
	v_cvt_pk_bf16_f32 v42, v42, v43
	s_waitcnt lgkmcnt(0)
	v_add_f32_e32 v32, v35, v50
	ds_bpermute_b32 v33, v125, v32
	v_cvt_pk_bf16_f32 v43, v52, v53
	global_store_dwordx4 v[48:49], v[40:43], off
	v_cvt_pk_bf16_f32 v34, v36, v37
	v_cvt_pk_bf16_f32 v35, v38, v39
	v_cvt_pk_bf16_f32 v36, v44, v45
	v_cvt_pk_bf16_f32 v37, v46, v47
	global_store_dwordx4 v[48:49], v[34:37], off offset:256
	s_and_saveexec_b64 s[18:19], s[2:3]
	s_cbranch_execz .LBB0_417
	v_lshl_add_u64 v[34:35], v[210:211], 2, s[14:15]
	s_waitcnt lgkmcnt(0)
	v_add_f32_e32 v32, v32, v33
	global_atomic_add_f32 v[34:35], v32, off
.LBB0_417:
	s_or_b64 exec, exec, s[18:19]
	v_mov_b32_e32 v36, v26
	v_mov_b32_e32 v37, v27
	v_mov_b32_e32 v26, v24
	v_mov_b32_e32 v27, v25
	v_mul_f32_e32 v24, v29, v29
	v_mul_f32_e32 v25, v31, v31
	v_fmac_f32_e32 v24, v28, v28
	v_fmac_f32_e32 v25, v30, v30
	v_add_f32_e32 v24, v24, v25
	v_mul_f32_e32 v25, v27, v27
	v_mul_f32_e32 v34, v37, v37
	v_fmac_f32_e32 v25, v26, v26
	v_fmac_f32_e32 v34, v36, v36
	v_add_f32_e32 v25, v25, v34
	v_add_f32_e32 v34, v24, v25
	v_cvt_pk_bf16_f32 v24, v28, v29
	v_cvt_pk_bf16_f32 v25, v30, v31
	v_mov_b32_e32 v28, v16
	v_mov_b32_e32 v29, v17
	v_mul_f32_e32 v16, v21, v21
	v_mul_f32_e32 v17, v23, v23
	v_mov_b32_e32 v30, v18
	v_mov_b32_e32 v31, v19
	v_fmac_f32_e32 v16, v20, v20
	v_fmac_f32_e32 v17, v22, v22
	v_add_f32_e32 v16, v16, v17
	v_mul_f32_e32 v17, v29, v29
	v_mul_f32_e32 v18, v31, v31
	v_fmac_f32_e32 v17, v28, v28
	v_fmac_f32_e32 v18, v30, v30
	v_add_f32_e32 v17, v17, v18
	v_add_f32_e32 v16, v16, v17
	v_add_f32_e32 v19, v34, v16
	ds_bpermute_b32 v34, v124, v19
	s_waitcnt lgkmcnt(1)
	v_lshlrev_b64 v[32:33], 10, v[208:209]
	v_lshl_add_u64 v[16:17], v[32:33], 1, s[12:13]
	v_lshl_add_u64 v[32:33], v[204:205], 1, v[16:17]
	v_cvt_pk_bf16_f32 v26, v26, v27
	s_waitcnt lgkmcnt(0)
	v_add_f32_e32 v16, v19, v34
	ds_bpermute_b32 v17, v125, v16
	v_cvt_pk_bf16_f32 v27, v36, v37
	global_store_dwordx4 v[32:33], v[24:27], off
	v_cvt_pk_bf16_f32 v18, v20, v21
	v_cvt_pk_bf16_f32 v19, v22, v23
	v_cvt_pk_bf16_f32 v20, v28, v29
	v_cvt_pk_bf16_f32 v21, v30, v31
	global_store_dwordx4 v[32:33], v[18:21], off offset:256
	s_and_saveexec_b64 s[18:19], s[2:3]
	s_cbranch_execz .LBB0_419
	v_lshl_add_u64 v[18:19], v[208:209], 2, s[14:15]
	s_waitcnt lgkmcnt(0)
	v_add_f32_e32 v16, v16, v17
	global_atomic_add_f32 v[18:19], v16, off
.LBB0_419:
	s_or_b64 exec, exec, s[18:19]
	v_mov_b32_e32 v20, v10
	v_mov_b32_e32 v21, v11
	v_mov_b32_e32 v10, v8
	v_mov_b32_e32 v11, v9
	v_mul_f32_e32 v8, v13, v13
	v_mul_f32_e32 v9, v15, v15
	v_fmac_f32_e32 v8, v12, v12
	v_fmac_f32_e32 v9, v14, v14
	v_add_f32_e32 v8, v8, v9
	v_mul_f32_e32 v9, v11, v11
	v_mul_f32_e32 v18, v21, v21
	v_fmac_f32_e32 v9, v10, v10
	v_fmac_f32_e32 v18, v20, v20
	v_add_f32_e32 v9, v9, v18
	v_add_f32_e32 v18, v8, v9
	v_cvt_pk_bf16_f32 v8, v12, v13
	v_cvt_pk_bf16_f32 v9, v14, v15
	v_mov_b32_e32 v12, v0
	v_mov_b32_e32 v13, v1
	v_mul_f32_e32 v0, v5, v5
	v_mul_f32_e32 v1, v7, v7
	v_mov_b32_e32 v14, v2
	v_mov_b32_e32 v15, v3
	v_fmac_f32_e32 v0, v4, v4
	v_fmac_f32_e32 v1, v6, v6
	v_add_f32_e32 v0, v0, v1
	v_mul_f32_e32 v1, v13, v13
	v_mul_f32_e32 v2, v15, v15
	v_fmac_f32_e32 v1, v12, v12
	v_fmac_f32_e32 v2, v14, v14
	v_add_f32_e32 v1, v1, v2
	v_add_f32_e32 v0, v0, v1
	v_add_f32_e32 v3, v18, v0
	ds_bpermute_b32 v18, v124, v3
	s_waitcnt lgkmcnt(1)
	v_lshlrev_b64 v[16:17], 10, v[206:207]
	v_lshl_add_u64 v[0:1], v[16:17], 1, s[12:13]
	v_lshl_add_u64 v[16:17], v[204:205], 1, v[0:1]
	v_cvt_pk_bf16_f32 v10, v10, v11
	s_waitcnt lgkmcnt(0)
	v_add_f32_e32 v0, v3, v18
	ds_bpermute_b32 v1, v125, v0
	v_cvt_pk_bf16_f32 v11, v20, v21
	global_store_dwordx4 v[16:17], v[8:11], off
	v_cvt_pk_bf16_f32 v2, v4, v5
	v_cvt_pk_bf16_f32 v3, v6, v7
	v_cvt_pk_bf16_f32 v4, v12, v13
	v_cvt_pk_bf16_f32 v5, v14, v15
	global_store_dwordx4 v[16:17], v[2:5], off offset:256
	s_and_saveexec_b64 s[18:19], s[2:3]
	s_cbranch_execz .LBB0_392
	v_lshl_add_u64 v[2:3], v[206:207], 2, s[14:15]
	s_waitcnt lgkmcnt(0)
	v_add_f32_e32 v0, v0, v1
	global_atomic_add_f32 v[2:3], v0, off
	s_branch .LBB0_392
